# v101: v100 + the first workgroup to arrive on each XCD issues an early L2 writeback (pre-cleans dirty lines before the last arriver's release)
# baseline (speedup 1.0000x reference)
.LBB0_138:
	s_or_b64 exec, exec, s[16:17]
	v_cvt_f32_u32_e32 v4, v2
	s_waitcnt vmcnt(0)
	v_readfirstlane_b32 s3, v3
	v_sub_u32_e32 v3, 0, v2
	v_rcp_iflag_f32_e32 v4, v4
	v_add_u32_e32 v5, s3, v1
	v_mul_f32_e32 v4, 0x4f7ffffe, v4
	v_cvt_u32_f32_e32 v4, v4
	v_mul_lo_u32 v1, v3, v4
	v_mul_hi_u32 v1, v4, v1
	v_add_u32_e32 v1, v4, v1
	v_mul_hi_u32 v1, v5, v1
	v_mul_lo_u32 v3, v1, v2
	v_sub_u32_e32 v3, v5, v3
	v_add_u32_e32 v4, 1, v1
	v_cmp_ge_u32_e32 vcc, v3, v2
	s_nop 1
	v_cndmask_b32_e32 v1, v1, v4, vcc
	v_sub_u32_e32 v4, v3, v2
	v_cndmask_b32_e32 v3, v3, v4, vcc
	v_add_u32_e32 v4, 1, v1
	v_cmp_ge_u32_e32 vcc, v3, v2
	v_add_u32_e32 v3, 1, v5
	s_nop 0
	v_cndmask_b32_e32 v1, v1, v4, vcc
	v_mul_lo_u32 v4, v2, v1
	v_add_u32_e32 v2, v4, v2
	v_cmp_ne_u32_e32 vcc, v3, v2
	v_add_u32_e32 v6, 1, v4
	v_cmp_eq_u32_e64 s[14:15], v3, v6
	s_waitcnt lgkmcnt(0)
	v_mul_lo_u32 v4, v1, v0
	v_add_u32_e32 v4, v4, v0
	v_mov_b32_e32 v5, 0x2480
	s_cbranch_vccnz .Lsb_nl0
	buffer_wbl2 sc1
	s_waitcnt vmcnt(0)
	s_add_u32 s16, s10, 0x62480
	s_addc_u32 s17, s11, 0
	v_mov_b32_e32 v6, 0
	v_mov_b32_e32 v7, 1
	global_atomic_add v6, v7, s[16:17]
	global_atomic_add v6, v7, s[16:17] offset:256
	global_atomic_add v6, v7, s[16:17] offset:512
	global_atomic_add v6, v7, s[16:17] offset:768
	global_atomic_add v6, v7, s[16:17] offset:1024
	global_atomic_add v6, v7, s[16:17] offset:1280
	global_atomic_add v6, v7, s[16:17] offset:1536
	global_atomic_add v6, v7, s[16:17] offset:1792
	global_atomic_add v6, v7, s[16:17] offset:2048
	global_atomic_add v6, v7, s[16:17] offset:2304
	global_atomic_add v6, v7, s[16:17] offset:2560
	global_atomic_add v6, v7, s[16:17] offset:2816
	global_atomic_add v6, v7, s[16:17] offset:3072
	global_atomic_add v6, v7, s[16:17] offset:3328
	global_atomic_add v6, v7, s[16:17] offset:3584
	global_atomic_add v6, v7, s[16:17] offset:3840
	s_branch .Lsb_poll0
.Lsb_nl0:
	s_and_b64 s[14:15], s[14:15], exec
	s_cbranch_scc0 .Lsb_poll0
	buffer_wbl2 sc1

.LBB0_430:
	s_or_b64 exec, exec, s[14:15]
	v_cvt_f32_u32_e32 v4, v2
	s_waitcnt vmcnt(0)
	v_readfirstlane_b32 s3, v3
	v_sub_u32_e32 v3, 0, v2
	v_rcp_iflag_f32_e32 v4, v4
	v_add_u32_e32 v5, s3, v1
	v_mul_f32_e32 v4, 0x4f7ffffe, v4
	v_cvt_u32_f32_e32 v4, v4
	v_mul_lo_u32 v1, v3, v4
	v_mul_hi_u32 v1, v4, v1
	v_add_u32_e32 v1, v4, v1
	v_mul_hi_u32 v1, v5, v1
	v_mul_lo_u32 v3, v1, v2
	v_sub_u32_e32 v3, v5, v3
	v_add_u32_e32 v4, 1, v1
	v_cmp_ge_u32_e32 vcc, v3, v2
	s_nop 1
	v_cndmask_b32_e32 v1, v1, v4, vcc
	v_sub_u32_e32 v4, v3, v2
	v_cndmask_b32_e32 v3, v3, v4, vcc
	v_add_u32_e32 v4, 1, v1
	v_cmp_ge_u32_e32 vcc, v3, v2
	v_add_u32_e32 v3, 1, v5
	s_nop 0
	v_cndmask_b32_e32 v1, v1, v4, vcc
	v_mul_lo_u32 v4, v2, v1
	v_add_u32_e32 v2, v4, v2
	v_cmp_ne_u32_e32 vcc, v3, v2
	v_add_u32_e32 v6, 1, v4
	v_cmp_eq_u32_e64 s[14:15], v3, v6
	s_waitcnt lgkmcnt(0)
	v_mul_lo_u32 v4, v1, v0
	v_add_u32_e32 v4, v4, v0
	v_mov_b32_e32 v5, 0x2480
	s_cbranch_vccnz .Lsb_nl4
	buffer_wbl2 sc1
	s_waitcnt vmcnt(0)
	s_add_u32 s16, s4, 0x62480
	s_addc_u32 s17, s5, 0
	v_mov_b32_e32 v6, 0
	v_mov_b32_e32 v7, 1
	global_atomic_add v6, v7, s[16:17]
	global_atomic_add v6, v7, s[16:17] offset:256
	global_atomic_add v6, v7, s[16:17] offset:512
	global_atomic_add v6, v7, s[16:17] offset:768
	global_atomic_add v6, v7, s[16:17] offset:1024
	global_atomic_add v6, v7, s[16:17] offset:1280
	global_atomic_add v6, v7, s[16:17] offset:1536
	global_atomic_add v6, v7, s[16:17] offset:1792
	global_atomic_add v6, v7, s[16:17] offset:2048
	global_atomic_add v6, v7, s[16:17] offset:2304
	global_atomic_add v6, v7, s[16:17] offset:2560
	global_atomic_add v6, v7, s[16:17] offset:2816
	global_atomic_add v6, v7, s[16:17] offset:3072
	global_atomic_add v6, v7, s[16:17] offset:3328
	global_atomic_add v6, v7, s[16:17] offset:3584
	global_atomic_add v6, v7, s[16:17] offset:3840
	s_branch .Lsb_poll4
